# memory-attention unit: cache touches of the first 16 V rows issued in front of the softmax, stacked on v80
# speedup vs baseline: 1.0011x; 1.0011x over previous
; __device__ __forceinline__ void memattn_unit(const Ctx& C, int r0, const float* kp0, const float* vp0, unsigned char* lds, int lane) {
;     ...
;     __syncthreads();
; #pragma unroll
;     for (int rr = 0; rr < 4; ++rr) {
;         float* row = logits + (4 * w + rr) * 256; float x[4]; float mx = -INFINITY;
; #pragma unroll
;         for (int j = 0; j < 4; ++j) { x[j] = row[lane + 64 * j]; mx = fmaxf(mx, x[j]); }
;         mx = wave_max(mx); float s = 0.f;
; #pragma unroll
;         for (int j = 0; j < 4; ++j) { x[j] = __builtin_amdgcn_exp2f(x[j] - mx); s += x[j]; }
;         s = wave_sum(s); const float is = 1.0f / s;
; #pragma unroll
;         for (int j = 0; j < 4; ++j) row[lane + 64 * j] = x[j] * is;
;     }
;     __syncthreads();
;     {
;         const int hw = w >> 1;
;         float acc[8][2];
; #pragma unroll
;         for (int qi = 0; qi < 8; ++qi) { acc[qi][0] = 0.f; acc[qi][1] = 0.f; }
;         const float* vbase = vp0 + 128 * w + 2 * lane;
;         float2 va[16];
; #pragma unroll
;         for (int u = 0; u < 16; ++u) va[u] = *(const float2*)(vbase + (size_t)u * 1024);
.LBB0_3210:
	s_lshl_b32 s99, s34, 20
	s_lshr_b32 s98, s34, 12
	s_add_u32 s99, s42, s99
	s_addc_u32 s98, s43, s98
	v_lshlrev_b32_e32 v244, 3, v117
	v_mov_b32_e32 v245, 0
	v_mov_b32_e32 v246, s99
	v_mov_b32_e32 v247, s98
	v_lshl_add_u64 v[244:245], v[246:247], 0, v[244:245]
	global_load_dwordx2 v[228:229], v[244:245], off
	v_lshl_add_u64 v[244:245], v[244:245], 0, s[26:27]
	global_load_dwordx2 v[230:231], v[244:245], off
	v_lshl_add_u64 v[244:245], v[244:245], 0, s[26:27]
	global_load_dwordx2 v[232:233], v[244:245], off
	v_lshl_add_u64 v[244:245], v[244:245], 0, s[26:27]
	global_load_dwordx2 v[234:235], v[244:245], off
	v_lshl_add_u64 v[244:245], v[244:245], 0, s[26:27]
	global_load_dwordx2 v[236:237], v[244:245], off
	v_lshl_add_u64 v[244:245], v[244:245], 0, s[26:27]
	global_load_dwordx2 v[238:239], v[244:245], off
	v_lshl_add_u64 v[244:245], v[244:245], 0, s[26:27]
	global_load_dwordx2 v[240:241], v[244:245], off
	v_lshl_add_u64 v[244:245], v[244:245], 0, s[26:27]
	global_load_dwordx2 v[242:243], v[244:245], off
	v_lshl_add_u64 v[244:245], v[244:245], 0, s[26:27]
	global_load_dwordx2 v[228:229], v[244:245], off
	v_lshl_add_u64 v[244:245], v[244:245], 0, s[26:27]
	global_load_dwordx2 v[230:231], v[244:245], off
	v_lshl_add_u64 v[244:245], v[244:245], 0, s[26:27]
	global_load_dwordx2 v[232:233], v[244:245], off
	v_lshl_add_u64 v[244:245], v[244:245], 0, s[26:27]
	global_load_dwordx2 v[234:235], v[244:245], off
	v_lshl_add_u64 v[244:245], v[244:245], 0, s[26:27]
	global_load_dwordx2 v[236:237], v[244:245], off
	v_lshl_add_u64 v[244:245], v[244:245], 0, s[26:27]
	global_load_dwordx2 v[238:239], v[244:245], off
	v_lshl_add_u64 v[244:245], v[244:245], 0, s[26:27]
	global_load_dwordx2 v[240:241], v[244:245], off
	v_lshl_add_u64 v[244:245], v[244:245], 0, s[26:27]
	global_load_dwordx2 v[242:243], v[244:245], off
	v_and_b32_e32 v0, 64, v116
	v_add_u32_e32 v8, 64, v0
	v_xor_b32_e32 v0, 1, v116
	v_cmp_lt_i32_e32 vcc, v0, v8
	v_lshl_add_u32 v9, v117, 2, s33
	s_waitcnt lgkmcnt(0)
	s_barrier
	v_cndmask_b32_e32 v4, v116, v0, vcc
	ds_read2st64_b32 v[0:1], v9 offset1:1
	ds_read2st64_b32 v[2:3], v9 offset0:2 offset1:3
	v_lshlrev_b32_e32 v10, 2, v4
	v_xor_b32_e32 v13, 2, v116
	v_cmp_lt_i32_e32 vcc, v13, v8
	s_waitcnt lgkmcnt(1)
	v_max3_f32 v11, v0, s53, v1
	s_waitcnt lgkmcnt(0)
	v_max3_f32 v11, v11, v2, v3
	ds_bpermute_b32 v12, v10, v11
	v_cndmask_b32_e32 v13, v116, v13, vcc
	v_lshlrev_b32_e32 v13, 2, v13
	v_xor_b32_e32 v14, 4, v116
	v_cmp_lt_i32_e32 vcc, v14, v8
	s_waitcnt lgkmcnt(0)
	v_max_f32_e32 v12, v12, v12
	v_max_f32_e32 v11, v11, v12
	ds_bpermute_b32 v12, v13, v11
	v_cndmask_b32_e32 v14, v116, v14, vcc
	v_lshlrev_b32_e32 v14, 2, v14
	v_xor_b32_e32 v15, 8, v116
	v_cmp_lt_i32_e32 vcc, v15, v8
	s_waitcnt lgkmcnt(0)
	v_max_f32_e32 v12, v12, v12
	v_max_f32_e32 v11, v11, v12
	ds_bpermute_b32 v12, v14, v11
	v_cndmask_b32_e32 v15, v116, v15, vcc
	v_lshlrev_b32_e32 v15, 2, v15
	v_xor_b32_e32 v16, 16, v116
	v_cmp_lt_i32_e32 vcc, v16, v8
	s_waitcnt lgkmcnt(0)
	v_max_f32_e32 v12, v12, v12
	v_max_f32_e32 v11, v11, v12
	ds_bpermute_b32 v12, v15, v11
	v_cndmask_b32_e32 v16, v116, v16, vcc
	v_lshlrev_b32_e32 v16, 2, v16
	v_xor_b32_e32 v17, 32, v116
	v_cmp_lt_i32_e32 vcc, v17, v8
	s_waitcnt lgkmcnt(0)
	v_max_f32_e32 v12, v12, v12
	v_max_f32_e32 v11, v11, v12
	ds_bpermute_b32 v12, v16, v11
	v_cndmask_b32_e32 v8, v116, v17, vcc
	v_lshlrev_b32_e32 v8, 2, v8
	ds_read2st64_b32 v[4:5], v9 offset0:4 offset1:5
	ds_read2st64_b32 v[6:7], v9 offset0:6 offset1:7
	s_ashr_i32 s35, s34, 31
	s_waitcnt lgkmcnt(2)
	v_max_f32_e32 v12, v12, v12
	v_max_f32_e32 v11, v11, v12
	ds_bpermute_b32 v12, v8, v11
	v_mov_b32_e32 v34, 0
	s_mov_b32 s4, s44
	v_mov_b32_e32 v35, v34
	v_mov_b32_e32 v58, v34
	s_waitcnt lgkmcnt(0)
	v_max_f32_e32 v12, v12, v12
	v_max_f32_e32 v11, v11, v12
	v_sub_f32_e32 v0, v0, v11
	v_exp_f32_e32 v12, v0
	v_sub_f32_e32 v0, v1, v11
	v_exp_f32_e32 v17, v0
	v_sub_f32_e32 v0, v2, v11
	v_exp_f32_e32 v18, v0
	v_sub_f32_e32 v0, v3, v11
	v_exp_f32_e32 v11, v0
	v_add_f32_e32 v0, 0, v12
	v_add_f32_e32 v0, v17, v0
	v_add_f32_e32 v0, v18, v0
	v_add_f32_e32 v0, v11, v0
	ds_bpermute_b32 v1, v10, v0
	v_max3_f32 v2, v4, s53, v5
	v_max3_f32 v2, v2, v6, v7
	ds_bpermute_b32 v3, v10, v2
	v_mov_b32_e32 v59, v34
	s_waitcnt lgkmcnt(1)
	v_add_f32_e32 v0, v0, v1
	ds_bpermute_b32 v1, v13, v0
	v_mov_b32_e32 v68, v34
	s_waitcnt lgkmcnt(1)
	v_max_f32_e32 v3, v3, v3
	v_max_f32_e32 v2, v2, v3
	ds_bpermute_b32 v3, v13, v2
	s_waitcnt lgkmcnt(1)
	v_add_f32_e32 v0, v0, v1
	ds_bpermute_b32 v1, v14, v0
	v_mov_b32_e32 v69, v34
	v_mov_b32_e32 v72, v34
	s_waitcnt lgkmcnt(1)
	v_max_f32_e32 v3, v3, v3
	v_max_f32_e32 v2, v2, v3
	s_waitcnt lgkmcnt(0)
	v_add_f32_e32 v0, v0, v1
	ds_bpermute_b32 v1, v15, v0
	ds_bpermute_b32 v3, v14, v2
	v_mov_b32_e32 v73, v34
	v_mov_b32_e32 v56, v34
	v_mov_b32_e32 v57, v34
	s_waitcnt lgkmcnt(1)
	v_add_f32_e32 v0, v0, v1
	s_waitcnt lgkmcnt(0)
	v_max_f32_e32 v1, v3, v3
	v_max_f32_e32 v1, v2, v1
	ds_bpermute_b32 v2, v15, v1
	ds_bpermute_b32 v3, v16, v0
	v_mov_b32_e32 v64, v34
	v_mov_b32_e32 v65, v34
	v_mov_b32_e32 v70, v34
	s_waitcnt lgkmcnt(1)
	v_max_f32_e32 v2, v2, v2
	v_max_f32_e32 v1, v1, v2
	s_waitcnt lgkmcnt(0)
	v_add_f32_e32 v0, v0, v3
	ds_bpermute_b32 v2, v16, v1
	ds_bpermute_b32 v3, v8, v0
	v_mov_b32_e32 v71, v34
	v_mov_b32_e32 v74, v34
	v_mov_b32_e32 v75, v34
	s_waitcnt lgkmcnt(1)
	v_max_f32_e32 v2, v2, v2
	s_waitcnt lgkmcnt(0)
	v_add_f32_e32 v19, v0, v3
	v_max_f32_e32 v0, v1, v2
	ds_bpermute_b32 v1, v8, v0
	v_div_scale_f32 v20, s[0:1], v19, v19, 1.0
	v_rcp_f32_e32 v21, v20
	v_div_scale_f32 v26, vcc, 1.0, v19, 1.0
	s_waitcnt lgkmcnt(0)
; __device__ __forceinline__ void memattn_unit(const Ctx& C, int r0, const float* kp0, const float* vp0, unsigned char* lds, int lane) {
;     ...
; #pragma unroll
;     for (int rr = 0; rr < 4; ++rr) {
;         float* row = logits + (4 * w + rr) * 256; float x[4]; float mx = -INFINITY;
; #pragma unroll
;         for (int j = 0; j < 4; ++j) { x[j] = row[lane + 64 * j]; mx = fmaxf(mx, x[j]); }
;         mx = wave_max(mx); float s = 0.f;
; #pragma unroll
;         for (int j = 0; j < 4; ++j) { x[j] = __builtin_amdgcn_exp2f(x[j] - mx); s += x[j]; }
;         s = wave_sum(s); const float is = 1.0f / s;
; #pragma unroll
;         for (int j = 0; j < 4; ++j) row[lane + 64 * j] = x[j] * is;
;     }
;     __syncthreads();
;     {
;         const int hw = w >> 1;
;         float acc[8][2];
; #pragma unroll
;         for (int qi = 0; qi < 8; ++qi) { acc[qi][0] = 0.f; acc[qi][1] = 0.f; }
;         const float* vbase = vp0 + 128 * w + 2 * lane;
;         float2 va[16];
; #pragma unroll
;         for (int u = 0; u < 16; ++u) va[u] = *(const float2*)(vbase + (size_t)u * 1024);
	v_max_f32_e32 v1, v1, v1
	v_max_f32_e32 v0, v0, v1
	v_sub_f32_e32 v1, v4, v0
	v_exp_f32_e32 v22, v1
	v_sub_f32_e32 v1, v5, v0
	v_exp_f32_e32 v23, v1
	v_sub_f32_e32 v1, v6, v0
	v_exp_f32_e32 v24, v1
	v_sub_f32_e32 v0, v7, v0
	v_exp_f32_e32 v25, v0
	v_add_f32_e32 v0, 0, v22
	v_add_f32_e32 v0, v23, v0
	v_add_f32_e32 v0, v24, v0
	v_add_f32_e32 v0, v25, v0
	ds_bpermute_b32 v1, v10, v0
	v_fma_f32 v2, -v20, v21, 1.0
	v_fmac_f32_e32 v21, v2, v21
	v_mul_f32_e32 v27, v26, v21
	v_fma_f32 v28, -v20, v27, v26
	s_waitcnt lgkmcnt(0)
	v_add_f32_e32 v29, v0, v1
	ds_read2st64_b32 v[0:1], v9 offset0:8 offset1:9
	ds_read2st64_b32 v[2:3], v9 offset0:10 offset1:11
	ds_bpermute_b32 v30, v13, v29
	v_fmac_f32_e32 v27, v28, v21
	v_fma_f32 v20, -v20, v27, v26
	s_waitcnt lgkmcnt(2)
	v_max3_f32 v31, v0, s53, v1
	s_waitcnt lgkmcnt(1)
	v_max3_f32 v31, v31, v2, v3
	ds_bpermute_b32 v32, v10, v31
	s_waitcnt lgkmcnt(1)
	v_add_f32_e32 v26, v29, v30
	ds_bpermute_b32 v28, v14, v26
	v_div_fmas_f32 v20, v20, v21, v27
	v_div_fixup_f32 v19, v20, v19, 1.0
	s_waitcnt lgkmcnt(1)
	v_max_f32_e32 v29, v32, v32
	v_max_f32_e32 v29, v31, v29
	ds_bpermute_b32 v30, v13, v29
	s_waitcnt lgkmcnt(1)
	v_add_f32_e32 v21, v26, v28
	ds_bpermute_b32 v26, v15, v21
	v_mul_f32_e32 v12, v12, v19
	v_mul_f32_e32 v17, v17, v19
	s_waitcnt lgkmcnt(1)
	v_max_f32_e32 v27, v30, v30
	v_max_f32_e32 v27, v29, v27
	ds_bpermute_b32 v28, v14, v27
	s_waitcnt lgkmcnt(1)
	v_add_f32_e32 v20, v21, v26
	ds_read2st64_b32 v[4:5], v9 offset0:12 offset1:13
	ds_read2st64_b32 v[6:7], v9 offset0:14 offset1:15
	ds_write2st64_b32 v9, v12, v17 offset1:1
	v_mul_f32_e32 v18, v18, v19
	s_waitcnt lgkmcnt(3)
	v_max_f32_e32 v26, v28, v28
	v_max_f32_e32 v26, v27, v26
	ds_bpermute_b32 v27, v15, v26
	v_mul_f32_e32 v11, v11, v19
	ds_write2st64_b32 v9, v18, v11 offset0:2 offset1:3
	s_waitcnt lgkmcnt(4)
	v_max3_f32 v18, v4, s53, v5
	s_waitcnt lgkmcnt(3)
	v_max3_f32 v18, v18, v6, v7
	s_waitcnt lgkmcnt(1)
	v_max_f32_e32 v12, v27, v27
	v_max_f32_e32 v12, v26, v12
	ds_bpermute_b32 v17, v16, v12
	ds_bpermute_b32 v19, v10, v18
	ds_bpermute_b32 v21, v16, v20
	s_waitcnt lgkmcnt(2)
	v_max_f32_e32 v17, v17, v17
	v_max_f32_e32 v12, v12, v17
	ds_bpermute_b32 v17, v8, v12
	s_waitcnt lgkmcnt(1)
	v_add_f32_e32 v20, v20, v21
	ds_bpermute_b32 v21, v8, v20
	s_waitcnt lgkmcnt(1)
	v_max_f32_e32 v17, v17, v17
	v_max_f32_e32 v12, v12, v17
	v_sub_f32_e32 v0, v0, v12
	v_sub_f32_e32 v1, v1, v12
	v_sub_f32_e32 v2, v2, v12
	v_sub_f32_e32 v3, v3, v12
	v_max_f32_e32 v12, v19, v19
	v_max_f32_e32 v12, v18, v12
	ds_bpermute_b32 v18, v13, v12
	v_exp_f32_e32 v0, v0
	v_exp_f32_e32 v1, v1
	v_exp_f32_e32 v2, v2
	v_exp_f32_e32 v3, v3
	s_waitcnt lgkmcnt(0)
	v_max_f32_e32 v18, v18, v18
	v_max_f32_e32 v12, v12, v18
	ds_bpermute_b32 v18, v14, v12
	v_add_f32_e32 v17, 0, v0
	v_add_f32_e32 v17, v1, v17
	v_add_f32_e32 v17, v2, v17
	v_add_f32_e32 v17, v3, v17
	s_waitcnt lgkmcnt(0)
	v_max_f32_e32 v18, v18, v18
	v_max_f32_e32 v12, v12, v18
	ds_bpermute_b32 v18, v15, v12
	ds_bpermute_b32 v19, v10, v17
	v_add_f32_e32 v20, v20, v21
	v_div_scale_f32 v21, s[0:1], v20, v20, 1.0
	s_waitcnt lgkmcnt(1)
	v_max_f32_e32 v18, v18, v18
	v_max_f32_e32 v12, v12, v18
	ds_bpermute_b32 v18, v16, v12
	s_waitcnt lgkmcnt(1)
	v_add_f32_e32 v17, v17, v19
	ds_bpermute_b32 v19, v13, v17
	v_rcp_f32_e32 v26, v21
	s_waitcnt lgkmcnt(1)
	v_max_f32_e32 v18, v18, v18
	v_max_f32_e32 v12, v12, v18
	ds_bpermute_b32 v18, v8, v12
	s_waitcnt lgkmcnt(1)
	v_add_f32_e32 v17, v17, v19
	ds_bpermute_b32 v19, v14, v17
	v_fma_f32 v11, -v21, v26, 1.0
	v_fmac_f32_e32 v26, v11, v26
	s_waitcnt lgkmcnt(1)
	v_max_f32_e32 v18, v18, v18
	v_max_f32_e32 v12, v12, v18
	v_sub_f32_e32 v4, v4, v12
	v_exp_f32_e32 v4, v4
	v_sub_f32_e32 v5, v5, v12
	s_waitcnt lgkmcnt(0)
	v_add_f32_e32 v17, v17, v19
	v_exp_f32_e32 v5, v5
	v_sub_f32_e32 v6, v6, v12
	ds_bpermute_b32 v19, v15, v17
	v_exp_f32_e32 v6, v6
	v_sub_f32_e32 v7, v7, v12
	v_exp_f32_e32 v7, v7
	v_add_f32_e32 v12, 0, v4
	v_add_f32_e32 v12, v5, v12
	v_add_f32_e32 v12, v6, v12
	s_waitcnt lgkmcnt(0)
	v_add_f32_e32 v17, v17, v19
	v_add_f32_e32 v12, v7, v12
	ds_bpermute_b32 v19, v16, v17
	ds_bpermute_b32 v10, v10, v12
	v_div_scale_f32 v11, vcc, 1.0, v20, 1.0
	v_mul_f32_e32 v27, v11, v26
	s_waitcnt lgkmcnt(1)
	v_add_f32_e32 v17, v17, v19
	s_waitcnt lgkmcnt(0)
	v_add_f32_e32 v10, v12, v10
	ds_bpermute_b32 v18, v8, v17
	ds_bpermute_b32 v12, v13, v10
	v_fma_f32 v28, -v21, v27, v11
	v_fmac_f32_e32 v27, v28, v26
	v_fma_f32 v11, -v21, v27, v11
	s_waitcnt lgkmcnt(1)
	v_add_f32_e32 v13, v17, v18
	s_waitcnt lgkmcnt(0)
	v_add_f32_e32 v10, v10, v12
	v_div_scale_f32 v17, s[0:1], v13, v13, 1.0
	ds_bpermute_b32 v12, v14, v10
	v_rcp_f32_e32 v18, v17
	v_div_fmas_f32 v11, v11, v26, v27
	v_div_fixup_f32 v11, v11, v20, 1.0
	v_mul_f32_e32 v20, v22, v11
	v_mul_f32_e32 v21, v23, v11
	v_mul_f32_e32 v19, v24, v11
	v_mul_f32_e32 v11, v25, v11
	ds_write2st64_b32 v9, v19, v11 offset0:6 offset1:7
	v_fma_f32 v11, -v17, v18, 1.0
	s_waitcnt lgkmcnt(1)
	v_add_f32_e32 v10, v10, v12
	v_fmac_f32_e32 v18, v11, v18
	ds_bpermute_b32 v11, v15, v10
	v_div_scale_f32 v12, vcc, 1.0, v13, 1.0
	v_mul_f32_e32 v14, v12, v18
	v_fma_f32 v15, -v17, v14, v12
	s_waitcnt lgkmcnt(0)
	v_add_f32_e32 v10, v10, v11
	ds_bpermute_b32 v11, v16, v10
	v_fmac_f32_e32 v14, v15, v18
	v_fma_f32 v12, -v17, v14, v12
	v_div_fmas_f32 v12, v12, v18, v14
	ds_write2st64_b32 v9, v20, v21 offset0:4 offset1:5
	s_waitcnt lgkmcnt(1)
	v_add_f32_e32 v10, v10, v11
	ds_bpermute_b32 v8, v8, v10
	v_div_fixup_f32 v11, v12, v13, 1.0
	v_mul_f32_e32 v0, v0, v11
	v_mul_f32_e32 v1, v1, v11
	ds_write2st64_b32 v9, v0, v1 offset0:8 offset1:9
	s_waitcnt lgkmcnt(1)
	v_add_f32_e32 v0, v10, v8
	v_div_scale_f32 v1, s[0:1], v0, v0, 1.0
	v_rcp_f32_e32 v8, v1
	v_mul_f32_e32 v2, v2, v11
	v_mul_f32_e32 v3, v3, v11
	ds_write2st64_b32 v9, v2, v3 offset0:10 offset1:11
	v_fma_f32 v2, -v1, v8, 1.0
	v_fmac_f32_e32 v8, v2, v8
	v_div_scale_f32 v2, vcc, 1.0, v0, 1.0
	v_mul_f32_e32 v3, v2, v8
	v_fma_f32 v10, -v1, v3, v2
	v_fmac_f32_e32 v3, v10, v8
	v_fma_f32 v1, -v1, v3, v2
	v_div_fmas_f32 v1, v1, v8, v3
	v_div_fixup_f32 v0, v1, v0, 1.0
	v_mul_f32_e32 v1, v4, v0
	v_mul_f32_e32 v2, v5, v0
	ds_write2st64_b32 v9, v1, v2 offset0:12 offset1:13
	v_mul_f32_e32 v1, v6, v0
	v_mul_f32_e32 v0, v7, v0
	s_lshl_b64 s[0:1], s[34:35], 20
	ds_write2st64_b32 v9, v1, v0 offset0:14 offset1:15
	s_add_u32 s0, s42, s0
	v_lshlrev_b32_e32 v0, 1, v117
	s_addc_u32 s1, s43, s1
	v_ashrrev_i32_e32 v1, 31, v0
	v_lshl_add_u64 v[2:3], v[0:1], 2, s[0:1]
	v_add_co_u32_e32 v4, vcc, s51, v2
	s_waitcnt lgkmcnt(0)
	s_nop 0
	v_addc_co_u32_e32 v5, vcc, 0, v3, vcc
	v_add_co_u32_e32 v6, vcc, s21, v2
	s_barrier
; __device__ __forceinline__ void memattn_unit(const Ctx& C, int r0, const float* kp0, const float* vp0, unsigned char* lds, int lane) {
;     ...
;         const float* vbase = vp0 + 128 * w + 2 * lane;
;         float2 va[16];
; #pragma unroll
;         for (int u = 0; u < 16; ++u) va[u] = *(const float2*)(vbase + (size_t)u * 1024);
	s_nop 0
	v_addc_co_u32_e32 v7, vcc, 0, v3, vcc
	global_load_dwordx2 v[54:55], v[4:5], off offset:-4096
	global_load_dwordx2 v[50:51], v[4:5], off
	global_load_dwordx2 v[48:49], v[6:7], off offset:-4096
	global_load_dwordx2 v[46:47], v[6:7], off
	v_add_co_u32_e32 v6, vcc, s54, v2
	s_mov_b32 s0, 0
	s_nop 0
	v_addc_co_u32_e32 v7, vcc, 0, v3, vcc
	v_add_co_u32_e32 v12, vcc, s55, v2
	s_nop 1
	v_addc_co_u32_e32 v13, vcc, 0, v3, vcc
	global_load_dwordx2 v[4:5], v[6:7], off offset:-4096
	global_load_dwordx2 v[10:11], v[6:7], off
	global_load_dwordx2 v[8:9], v[12:13], off offset:-4096
	s_nop 0
	global_load_dwordx2 v[6:7], v[12:13], off
	v_add_co_u32_e32 v12, vcc, s56, v2
	s_nop 1
	v_addc_co_u32_e32 v13, vcc, 0, v3, vcc
	v_add_co_u32_e32 v20, vcc, s57, v2
	s_nop 1
	v_addc_co_u32_e32 v21, vcc, 0, v3, vcc
	global_load_dwordx2 v[18:19], v[12:13], off offset:-4096
	global_load_dwordx2 v[16:17], v[12:13], off
	global_load_dwordx2 v[14:15], v[20:21], off offset:-4096
	s_nop 0
	global_load_dwordx2 v[12:13], v[20:21], off
	v_add_co_u32_e32 v20, vcc, 0xd000, v2
	s_nop 1
	v_addc_co_u32_e32 v21, vcc, 0, v3, vcc
	v_add_co_u32_e32 v22, vcc, 0xe000, v2
	s_nop 1
	v_addc_co_u32_e32 v23, vcc, 0, v3, vcc
	v_add_co_u32_e32 v26, vcc, 0xf000, v2
	s_nop 1
	v_addc_co_u32_e32 v27, vcc, 0, v3, vcc
	global_load_dwordx2 v[82:83], v[2:3], off
	global_load_dwordx2 v[24:25], v[20:21], off
	s_nop 0
	global_load_dwordx2 v[22:23], v[22:23], off
	s_nop 0
	global_load_dwordx2 v[20:21], v[26:27], off
